# P11 attention equal-work dealing: second unit takes mirrored query block (v29 + attnpair)
# baseline (speedup 1.0000x reference)
.LBB0_1332:
	v_cvt_pk_bf16_f32 v1, v64, v0
	ds_write_b16 v197, v1 offset:36864
	v_cvt_pk_bf16_f32 v1, v48, v0
	ds_write_b16 v197, v1 offset:36928
	v_cvt_pk_bf16_f32 v1, v32, v0
	ds_write_b16 v197, v1 offset:36992
	v_cvt_pk_bf16_f32 v1, v16, v0
	ds_write_b16 v197, v1 offset:37056
	v_cvt_pk_bf16_f32 v1, v65, v0
	ds_write_b16 v197, v1 offset:37136
	v_cvt_pk_bf16_f32 v1, v49, v0
	ds_write_b16 v197, v1 offset:37200
	v_cvt_pk_bf16_f32 v1, v33, v0
	ds_write_b16 v197, v1 offset:37264
	v_cvt_pk_bf16_f32 v1, v17, v0
	ds_write_b16 v197, v1 offset:37328
	v_cvt_pk_bf16_f32 v1, v66, v0
	ds_write_b16 v197, v1 offset:37408
	v_cvt_pk_bf16_f32 v1, v50, v0
	ds_write_b16 v197, v1 offset:37472
	v_cvt_pk_bf16_f32 v1, v34, v0
	ds_write_b16 v197, v1 offset:37536
	v_cvt_pk_bf16_f32 v1, v18, v0
	ds_write_b16 v197, v1 offset:37600
	v_cvt_pk_bf16_f32 v1, v67, v0
	ds_write_b16 v197, v1 offset:37680
	v_cvt_pk_bf16_f32 v1, v51, v0
	ds_write_b16 v197, v1 offset:37744
	v_cvt_pk_bf16_f32 v1, v35, v0
	ds_write_b16 v197, v1 offset:37808
	v_cvt_pk_bf16_f32 v1, v19, v0
	ds_write_b16 v197, v1 offset:37872
	v_cvt_pk_bf16_f32 v1, v68, v0
	ds_write_b16 v197, v1 offset:39040
	v_cvt_pk_bf16_f32 v1, v52, v0
	ds_write_b16 v197, v1 offset:39104
	v_cvt_pk_bf16_f32 v1, v36, v0
	ds_write_b16 v197, v1 offset:39168
	v_cvt_pk_bf16_f32 v1, v20, v0
	ds_write_b16 v197, v1 offset:39232
	v_cvt_pk_bf16_f32 v1, v69, v0
	ds_write_b16 v197, v1 offset:39312
	v_cvt_pk_bf16_f32 v1, v53, v0
	ds_write_b16 v197, v1 offset:39376
	v_cvt_pk_bf16_f32 v1, v37, v0
	ds_write_b16 v197, v1 offset:39440
	v_cvt_pk_bf16_f32 v1, v21, v0
	ds_write_b16 v197, v1 offset:39504
	v_cvt_pk_bf16_f32 v1, v70, v0
	ds_write_b16 v197, v1 offset:39584
	v_cvt_pk_bf16_f32 v1, v54, v0
	ds_write_b16 v197, v1 offset:39648
	v_cvt_pk_bf16_f32 v1, v38, v0
	ds_write_b16 v197, v1 offset:39712
	v_cvt_pk_bf16_f32 v1, v22, v0
	ds_write_b16 v197, v1 offset:39776
	v_cvt_pk_bf16_f32 v1, v71, v0
	ds_write_b16 v197, v1 offset:39856
	v_cvt_pk_bf16_f32 v1, v55, v0
	ds_write_b16 v197, v1 offset:39920
	v_cvt_pk_bf16_f32 v1, v39, v0
	ds_write_b16 v197, v1 offset:39984
	v_cvt_pk_bf16_f32 v1, v23, v0
	ds_write_b16 v197, v1 offset:40048
	v_cvt_pk_bf16_f32 v1, v72, v0
	ds_write_b16 v197, v1 offset:41216
	v_cvt_pk_bf16_f32 v1, v56, v0
	ds_write_b16 v197, v1 offset:41280
	v_cvt_pk_bf16_f32 v1, v40, v0
	ds_write_b16 v197, v1 offset:41344
	v_cvt_pk_bf16_f32 v1, v24, v0
	ds_write_b16 v197, v1 offset:41408
	v_cvt_pk_bf16_f32 v1, v73, v0
	ds_write_b16 v197, v1 offset:41488
	v_cvt_pk_bf16_f32 v1, v57, v0
	ds_write_b16 v197, v1 offset:41552
	v_cvt_pk_bf16_f32 v1, v41, v0
	ds_write_b16 v197, v1 offset:41616
	v_cvt_pk_bf16_f32 v1, v25, v0
	ds_write_b16 v197, v1 offset:41680
	v_cvt_pk_bf16_f32 v1, v74, v0
	ds_write_b16 v197, v1 offset:41760
	v_cvt_pk_bf16_f32 v1, v58, v0
	ds_write_b16 v197, v1 offset:41824
	v_cvt_pk_bf16_f32 v1, v42, v0
	ds_write_b16 v197, v1 offset:41888
	v_cvt_pk_bf16_f32 v1, v26, v0
	ds_write_b16 v197, v1 offset:41952
	v_cvt_pk_bf16_f32 v1, v75, v0
	ds_write_b16 v197, v1 offset:42032
	v_cvt_pk_bf16_f32 v1, v59, v0
	ds_write_b16 v197, v1 offset:42096
	v_cvt_pk_bf16_f32 v1, v43, v0
	ds_write_b16 v197, v1 offset:42160
	v_cvt_pk_bf16_f32 v1, v27, v0
	ds_write_b16 v197, v1 offset:42224
	v_cvt_pk_bf16_f32 v1, v76, v0
	ds_write_b16 v197, v1 offset:43392
	v_cvt_pk_bf16_f32 v1, v60, v0
	ds_write_b16 v197, v1 offset:43456
	v_cvt_pk_bf16_f32 v1, v44, v0
	ds_write_b16 v197, v1 offset:43520
	v_cvt_pk_bf16_f32 v1, v28, v0
	ds_write_b16 v197, v1 offset:43584
	v_cvt_pk_bf16_f32 v1, v77, v0
	ds_write_b16 v197, v1 offset:43664
	v_cvt_pk_bf16_f32 v1, v61, v0
	ds_write_b16 v197, v1 offset:43728
	v_cvt_pk_bf16_f32 v1, v45, v0
	ds_write_b16 v197, v1 offset:43792
	v_cvt_pk_bf16_f32 v1, v29, v0
	ds_write_b16 v197, v1 offset:43856
	v_cvt_pk_bf16_f32 v1, v78, v0
	ds_write_b16 v197, v1 offset:43936
	v_cvt_pk_bf16_f32 v1, v62, v0
	s_add_i32 s10, s37, s22
	ds_write_b16 v197, v1 offset:44000
	v_cvt_pk_bf16_f32 v1, v46, v0
	s_ashr_i32 s11, s10, 31
	ds_write_b16 v197, v1 offset:44064
	v_cvt_pk_bf16_f32 v1, v30, v0
	s_lshl_b64 s[10:11], s[10:11], 12
	ds_write_b16 v197, v1 offset:44128
	v_cvt_pk_bf16_f32 v1, v79, v0
	s_add_u32 s10, s18, s10
	ds_write_b16 v197, v1 offset:44208
	v_cvt_pk_bf16_f32 v1, v63, v0
	s_addc_u32 s11, s19, s11
	ds_write_b16 v197, v1 offset:44272
	v_cvt_pk_bf16_f32 v1, v47, v0
	s_lshl_b32 s12, s31, 1
	ds_write_b16 v197, v1 offset:44336
	v_cvt_pk_bf16_f32 v1, v31, v0
	ds_write_b16 v197, v1 offset:44400
	s_add_u32 s10, s10, s12
	s_addc_u32 s11, s11, 0
	s_waitcnt lgkmcnt(0)
	v_mov_b32_e32 v169, v0
	v_lshl_add_u64 v[6:7], s[10:11], 0, v[168:169]
	ds_read_b128 v[2:5], v212 offset:36864
	v_lshl_add_u64 v[10:11], v[6:7], 0, s[16:17]
	ds_read_b128 v[6:9], v212 offset:37952
	v_mov_b32_e32 v171, v0
	v_lshl_add_u64 v[12:13], v[10:11], 0, v[170:171]
	v_mov_b32_e32 v173, v0
	s_waitcnt lgkmcnt(1)
	global_store_dwordx4 v[12:13], v[2:5], off
	v_lshl_add_u64 v[12:13], v[10:11], 0, v[172:173]
	ds_read_b128 v[2:5], v212 offset:39040
	s_waitcnt lgkmcnt(1)
	global_store_dwordx4 v[12:13], v[6:9], off
	ds_read_b128 v[6:9], v212 offset:40128
	v_mov_b32_e32 v175, v0
	v_lshl_add_u64 v[12:13], v[10:11], 0, v[174:175]
	v_mov_b32_e32 v177, v0
	s_waitcnt lgkmcnt(1)
	global_store_dwordx4 v[12:13], v[2:5], off
	v_lshl_add_u64 v[12:13], v[10:11], 0, v[176:177]
	ds_read_b128 v[2:5], v212 offset:41216
	s_waitcnt lgkmcnt(1)
	global_store_dwordx4 v[12:13], v[6:9], off
	ds_read_b128 v[6:9], v212 offset:42304
	v_mov_b32_e32 v179, v0
	v_lshl_add_u64 v[12:13], v[10:11], 0, v[178:179]
	v_mov_b32_e32 v181, v0
	s_waitcnt lgkmcnt(1)
	global_store_dwordx4 v[12:13], v[2:5], off
	v_lshl_add_u64 v[12:13], v[10:11], 0, v[180:181]
	ds_read_b128 v[2:5], v212 offset:43392
	s_waitcnt lgkmcnt(1)
	global_store_dwordx4 v[12:13], v[6:9], off
	ds_read_b128 v[6:9], v212 offset:44480
	v_mov_b32_e32 v183, v0
	v_lshl_add_u64 v[12:13], v[10:11], 0, v[182:183]
	v_mov_b32_e32 v185, v0
	s_add_i32 s30, s30, s52
	s_cmpk_eq_i32 s52, 0x100
	s_cselect_b32 s26, 15, 0
	s_xor_b32 s30, s30, s26
	s_lshl_b32 s25, s30, 8
	s_lshl_b32 s27, s30, 4
	s_lshl_b32 s29, s30, 3
	s_waitcnt lgkmcnt(1)
	global_store_dwordx4 v[12:13], v[2:5], off
	s_cmpk_gt_i32 s30, 0x1ff
	s_nop 0
	v_lshl_add_u64 v[2:3], v[10:11], 0, v[184:185]
	s_waitcnt lgkmcnt(0)
	global_store_dwordx4 v[2:3], v[6:9], off
	s_barrier
	s_cbranch_scc1 .LBB0_1349
